# K=2816 sample-row task: residual element loaded before the MFMA stream instead of after the reduction barrier
# baseline (speedup 1.0000x reference)
.LBB0_670:
	v_mov_b32_e32 v84, v201
	s_movk_i32 s2, 0x160
	v_ashrrev_i32_e32 v85, 6, v84
	v_and_b32_e32 v0, 15, v84
	v_mov_b64_e32 v[2:3], s[6:7]
	v_lshrrev_b32_e32 v4, 1, v84
	v_mul_lo_u32 v5, v85, s2
	v_mul_u32_u24_e32 v6, 0xb00, v0
	v_add_u32_e32 v7, s8, v0
	v_and_or_b32 v4, v4, 24, v5
	v_lshlrev_b32_e32 v0, 1, v6
	v_mad_i64_i32 v[2:3], s[10:11], v7, s14, v[2:3]
	v_lshl_add_u64 v[6:7], s[4:5], 0, v[0:1]
	v_ashrrev_i32_e32 v5, 31, v4
	v_add_u32_e32 v8, 32, v4
	v_add_u32_e32 v10, 64, v4
	v_add_u32_e32 v12, 0x60, v4
	v_add_u32_e32 v14, 0x80, v4
	s_mov_b64 s[10:11], 0x16000
	v_add_u32_e32 v16, 0xa0, v4
	v_add_u32_e32 v18, 0xc0, v4
	v_add_u32_e32 v20, 0xe0, v4
	v_add_u32_e32 v22, 0x100, v4
	v_add_u32_e32 v24, 0x120, v4
	v_add_u32_e32 v26, 0x140, v4
	v_lshl_add_u64 v[28:29], v[6:7], 0, s[10:11]
	v_lshlrev_b64 v[4:5], 1, v[4:5]
	v_ashrrev_i32_e32 v9, 31, v8
	v_ashrrev_i32_e32 v11, 31, v10
	v_ashrrev_i32_e32 v13, 31, v12
	v_ashrrev_i32_e32 v15, 31, v14
	v_ashrrev_i32_e32 v17, 31, v16
	v_ashrrev_i32_e32 v19, 31, v18
	v_ashrrev_i32_e32 v21, 31, v20
	v_ashrrev_i32_e32 v23, 31, v22
	v_ashrrev_i32_e32 v25, 31, v24
	v_ashrrev_i32_e32 v27, 31, v26
	v_lshl_add_u64 v[30:31], v[28:29], 0, v[4:5]
	v_lshl_add_u64 v[72:73], v[2:3], 0, v[4:5]
	v_lshl_add_u64 v[32:33], v[8:9], 1, v[28:29]
	v_lshl_add_u64 v[34:35], v[10:11], 1, v[28:29]
	v_lshl_add_u64 v[46:47], v[12:13], 1, v[28:29]
	v_lshl_add_u64 v[58:59], v[14:15], 1, v[28:29]
	s_barrier
	v_lshl_add_u64 v[70:71], v[6:7], 0, v[4:5]
	v_lshl_add_u64 v[66:67], v[16:17], 1, v[28:29]
	v_lshl_add_u64 v[74:75], v[18:19], 1, v[28:29]
	v_lshl_add_u64 v[76:77], v[20:21], 1, v[28:29]
	v_lshl_add_u64 v[78:79], v[22:23], 1, v[28:29]
	v_lshl_add_u64 v[80:81], v[24:25], 1, v[28:29]
	v_lshl_add_u64 v[82:83], v[26:27], 1, v[28:29]
	global_load_dwordx4 v[86:89], v[72:73], off
	global_load_dwordx4 v[90:93], v[70:71], off
	global_load_dwordx4 v[94:97], v[30:31], off
	global_load_dwordx4 v[98:101], v[72:73], off offset:64
	global_load_dwordx4 v[102:105], v[70:71], off offset:64
	global_load_dwordx4 v[106:109], v[32:33], off
	global_load_dwordx4 v[110:113], v[72:73], off offset:128
	global_load_dwordx4 v[114:117], v[70:71], off offset:128
	global_load_dwordx4 v[118:121], v[34:35], off
	global_load_dwordx4 v[122:125], v[72:73], off offset:192
	global_load_dwordx4 v[126:129], v[70:71], off offset:192
	global_load_dwordx4 v[130:133], v[46:47], off
	global_load_dwordx4 v[134:137], v[72:73], off offset:256
	global_load_dwordx4 v[138:141], v[70:71], off offset:256
	global_load_dwordx4 v[142:145], v[58:59], off
	global_load_dwordx4 v[146:149], v[72:73], off offset:320
	global_load_dwordx4 v[150:153], v[70:71], off offset:320
	global_load_dwordx4 v[154:157], v[66:67], off
	global_load_dwordx4 v[158:161], v[72:73], off offset:384
	global_load_dwordx4 v[162:165], v[70:71], off offset:384
	global_load_dwordx4 v[166:169], v[74:75], off
	global_load_dwordx4 v[170:173], v[72:73], off offset:448
	global_load_dwordx4 v[174:177], v[70:71], off offset:448
	global_load_dwordx4 v[178:181], v[76:77], off
	global_load_dwordx4 v[182:185], v[72:73], off offset:512
	global_load_dwordx4 v[186:189], v[70:71], off offset:512
	global_load_dwordx4 v[190:193], v[78:79], off
	global_load_dwordx4 v[202:205], v[72:73], off offset:576
	global_load_dwordx4 v[206:209], v[70:71], off offset:576
	global_load_dwordx4 v[210:213], v[80:81], off
	global_load_dwordx4 v[214:217], v[72:73], off offset:640
	global_load_dwordx4 v[218:221], v[70:71], off offset:640
	global_load_dwordx4 v[222:225], v[82:83], off
	v_lshlrev_b32_e32 v0, 4, v84
	v_and_b32_e32 v0, 0x3f0, v0
	s_and_b32 s10, s8, 0xffffffe0
	s_ashr_i32 s11, s10, 31
	s_lshr_b32 s2, s8, 1
	s_and_b32 s2, s2, 8
	s_add_i32 s9, s9, s12
	s_add_i32 s8, s8, s13
	s_cmp_gt_i32 s9, 63
	v_ashrrev_i32_e32 v24, 8, v84
	v_bfe_u32 v22, v84, 2, 4
	v_lshl_or_b32 v22, v24, 4, v22
	v_lshlrev_b32_e32 v23, 11, v85
	v_add_u32_e32 v22, 0x8000, v22
	v_add3_u32 v27, 0, v23, v0
	v_ashrrev_i32_e32 v23, 31, v22
	v_lshrrev_b32_e32 v25, 2, v84
	v_and_b32_e32 v0, 48, v25
	v_and_b32_e32 v26, 3, v84
	v_lshlrev_b64 v[10:11], 11, v[22:23]
	v_lshl_add_u64 v[10:11], s[16:17], 0, v[10:11]
	v_lshl_add_u64 v[10:11], s[10:11], 1, v[10:11]
	v_lshl_add_u64 v[10:11], v[10:11], 0, v[0:1]
	v_lshlrev_b32_e32 v0, 1, v26
	v_lshl_add_u64 v[10:11], v[10:11], 0, s[2:3]
	v_lshl_add_u64 v[10:11], v[10:11], 0, v[0:1]
	global_load_ushort v12, v[10:11], off
	s_waitcnt vmcnt(32)
	v_mfma_f32_16x16x32_bf16 v[6:9], v[86:89], v[90:93], 0
	s_waitcnt vmcnt(31)
	v_mfma_f32_16x16x32_bf16 v[2:5], v[86:89], v[94:97], 0
	s_waitcnt vmcnt(29)
	v_mfma_f32_16x16x32_bf16 v[6:9], v[98:101], v[102:105], v[6:9]
	s_waitcnt vmcnt(28)
	v_mfma_f32_16x16x32_bf16 v[2:5], v[98:101], v[106:109], v[2:5]
	s_waitcnt vmcnt(26)
	v_mfma_f32_16x16x32_bf16 v[6:9], v[110:113], v[114:117], v[6:9]
	s_waitcnt vmcnt(25)
	v_mfma_f32_16x16x32_bf16 v[2:5], v[110:113], v[118:121], v[2:5]
	s_waitcnt vmcnt(23)
	v_mfma_f32_16x16x32_bf16 v[6:9], v[122:125], v[126:129], v[6:9]
	s_waitcnt vmcnt(22)
	v_mfma_f32_16x16x32_bf16 v[2:5], v[122:125], v[130:133], v[2:5]
	s_waitcnt vmcnt(20)
	v_mfma_f32_16x16x32_bf16 v[6:9], v[134:137], v[138:141], v[6:9]
	s_waitcnt vmcnt(19)
	v_mfma_f32_16x16x32_bf16 v[2:5], v[134:137], v[142:145], v[2:5]
	s_waitcnt vmcnt(17)
	v_mfma_f32_16x16x32_bf16 v[6:9], v[146:149], v[150:153], v[6:9]
	s_waitcnt vmcnt(16)
	v_mfma_f32_16x16x32_bf16 v[2:5], v[146:149], v[154:157], v[2:5]
	s_waitcnt vmcnt(14)
	v_mfma_f32_16x16x32_bf16 v[6:9], v[158:161], v[162:165], v[6:9]
	s_waitcnt vmcnt(13)
	v_mfma_f32_16x16x32_bf16 v[2:5], v[158:161], v[166:169], v[2:5]
	s_waitcnt vmcnt(11)
	v_mfma_f32_16x16x32_bf16 v[6:9], v[170:173], v[174:177], v[6:9]
	s_waitcnt vmcnt(10)
	v_mfma_f32_16x16x32_bf16 v[2:5], v[170:173], v[178:181], v[2:5]
	s_waitcnt vmcnt(8)
	v_mfma_f32_16x16x32_bf16 v[6:9], v[182:185], v[186:189], v[6:9]
	s_waitcnt vmcnt(7)
	v_mfma_f32_16x16x32_bf16 v[2:5], v[182:185], v[190:193], v[2:5]
	s_waitcnt vmcnt(5)
	v_mfma_f32_16x16x32_bf16 v[6:9], v[202:205], v[206:209], v[6:9]
	s_waitcnt vmcnt(4)
	v_mfma_f32_16x16x32_bf16 v[2:5], v[202:205], v[210:213], v[2:5]
	s_waitcnt vmcnt(2)
	v_mfma_f32_16x16x32_bf16 v[6:9], v[214:217], v[218:221], v[6:9]
	s_waitcnt vmcnt(1)
	v_mfma_f32_16x16x32_bf16 v[2:5], v[214:217], v[222:225], v[2:5]
	s_nop 4
	ds_write_b128 v27, v[6:9]
	s_nop 1
	ds_write_b128 v27, v[2:5] offset:1024
	s_waitcnt lgkmcnt(0)
	s_barrier
	v_lshlrev_b32_e32 v2, 2, v84
	v_lshl_add_u32 v3, v26, 2, 0
	v_lshlrev_b32_e32 v4, 10, v24
	v_and_b32_e32 v2, 0x3f0, v2
	v_add3_u32 v8, v3, v4, v2
	ds_read2st64_b32 v[2:3], v8 offset1:8
	ds_read2st64_b32 v[4:5], v8 offset0:16 offset1:24
	ds_read2st64_b32 v[6:7], v8 offset0:32 offset1:40
	ds_read2st64_b32 v[8:9], v8 offset0:48 offset1:56
	s_waitcnt lgkmcnt(3)
	v_add_f32_e32 v2, 0, v2
	v_add_f32_e32 v2, v2, v3
	s_waitcnt lgkmcnt(2)
	v_add_f32_e32 v2, v2, v4
	v_add_f32_e32 v2, v2, v5
	s_waitcnt lgkmcnt(1)
	v_add_f32_e32 v2, v2, v6
	v_add_f32_e32 v2, v2, v7
	s_waitcnt lgkmcnt(0)
	v_add_f32_e32 v2, v2, v8
	v_add_f32_e32 v2, v2, v9
	s_waitcnt vmcnt(0)
	v_lshlrev_b32_e32 v0, 16, v12
	v_fmac_f32_e32 v0, 0.5, v2
	v_cvt_pk_bf16_f32 v0, v0, v1
	global_store_short v[10:11], v0, off
	s_cbranch_scc0 .LBB0_670
